# SWA attention key-tile loop hand-pipelined like the MLA loop: K fragments read up front with counted lgkmcnt, V fragments prefetched, exp/cvt interleaved with PV MFMAs
# speedup vs baseline: 1.0127x; 1.0025x over previous
.LBB0_462:
	s_bitcmp1_b32 s10, 0
	s_cselect_b32 s19, 0x6400, 0
	v_add_u32_e32 v0, s19, v109
	v_add_u32_e32 v234, s19, v108
	ds_read_b128 v[148:151], v0
	ds_read_b128 v[152:155], v0 offset:4608
	ds_read_b128 v[156:159], v0 offset:32
	ds_read_b128 v[160:163], v0 offset:4640
	ds_read_b128 v[164:167], v0 offset:64
	ds_read_b128 v[168:171], v0 offset:4672
	ds_read_b128 v[172:175], v0 offset:96
	ds_read_b128 v[176:179], v0 offset:4704
	s_add_i32 s18, s10, 1
	s_cmp_lt_i32 s18, s38
	s_cselect_b64 s[16:17], -1, 0
	s_cmp_ge_i32 s18, s38
	s_cbranch_scc1 .LBB0_464
	s_cmp_lt_i32 s18, s24
	s_cselect_b32 s11, 0, s24
	s_cselect_b32 s19, s33, s25
	s_lshl_b32 s11, s11, 6
	s_sub_i32 s11, s19, s11
	v_add_u32_e32 v34, s11, v111
	v_ashrrev_i32_e32 v35, 31, v34
	v_lshlrev_b64 v[34:35], 8, v[34:35]
	v_lshl_add_u64 v[36:37], v[102:103], 0, v[34:35]
	v_lshl_add_u64 v[34:35], v[104:105], 0, v[34:35]
	global_load_dwordx4 v[86:89], v[36:37], off
	global_load_dwordx4 v[90:93], v[34:35], off
.LBB0_464:
	v_mov_b64_e32 v[50:51], v[94:95]
	v_mov_b64_e32 v[52:53], v[96:97]
	v_mfma_f32_32x32x16_bf16 v[34:49], v[82:85], v[94:97], 0
	s_cmp_ge_i32 s10, s24
	s_cselect_b64 s[10:11], -1, 0
	s_xor_b64 s[62:63], s[30:31], -1
	s_or_b64 s[10:11], s[62:63], s[10:11]
	s_and_b64 vcc, exec, s[10:11]
	v_mfma_f32_32x32x16_bf16 v[50:65], v[82:85], v[50:53], 0
	s_waitcnt lgkmcnt(6)
	v_mfma_f32_32x32x16_bf16 v[34:49], v[148:151], v[66:69], v[34:49]
	v_mfma_f32_32x32x16_bf16 v[50:65], v[152:155], v[66:69], v[50:65]
	s_waitcnt lgkmcnt(4)
	v_mfma_f32_32x32x16_bf16 v[34:49], v[156:159], v[70:73], v[34:49]
	v_mfma_f32_32x32x16_bf16 v[50:65], v[160:163], v[70:73], v[50:65]
	s_waitcnt lgkmcnt(2)
	v_mfma_f32_32x32x16_bf16 v[34:49], v[164:167], v[74:77], v[34:49]
	v_mfma_f32_32x32x16_bf16 v[50:65], v[168:171], v[74:77], v[50:65]
	s_waitcnt lgkmcnt(0)
	v_mfma_f32_32x32x16_bf16 v[34:49], v[172:175], v[78:81], v[34:49]
	v_mfma_f32_32x32x16_bf16 v[50:65], v[176:179], v[78:81], v[50:65]
	ds_read_b64_tr_b16 v[180:181], v234 offset:13312
	ds_read_b64_tr_b16 v[182:183], v234 offset:14848
	ds_read_b64_tr_b16 v[184:185], v234 offset:16384
	ds_read_b64_tr_b16 v[186:187], v234 offset:17920
	ds_read_b64_tr_b16 v[188:189], v234 offset:19456
	ds_read_b64_tr_b16 v[190:191], v234 offset:20992
	ds_read_b64_tr_b16 v[192:193], v234 offset:22528
	ds_read_b64_tr_b16 v[194:195], v234 offset:24064
	s_cbranch_vccnz .LBB0_466
	v_add_u32_e32 v0, 59, v110
	v_cmp_lt_u32_e32 vcc, s6, v0
	v_add_u32_e32 v0, 27, v110
	s_nop 4
	v_cndmask_b32_e32 v34, v248, v34, vcc
	v_cmp_lt_u32_e32 vcc, s6, v0
	v_add_u32_e32 v0, 58, v110
	s_nop 0
	v_cndmask_b32_e32 v50, v248, v50, vcc
	v_cmp_lt_u32_e32 vcc, s6, v0
	v_add_u32_e32 v0, 26, v110
	s_nop 0
	v_cndmask_b32_e32 v35, v248, v35, vcc
	v_cmp_lt_u32_e32 vcc, s6, v0
	v_add_u32_e32 v0, 57, v110
	s_nop 0
	v_cndmask_b32_e32 v51, v248, v51, vcc
	v_cmp_lt_u32_e32 vcc, s6, v0
	v_add_u32_e32 v0, 25, v110
	s_nop 0
	v_cndmask_b32_e32 v36, v248, v36, vcc
	v_cmp_lt_u32_e32 vcc, s6, v0
	v_add_u32_e32 v0, 56, v110
	s_nop 0
	v_cndmask_b32_e32 v52, v248, v52, vcc
	v_cmp_lt_u32_e32 vcc, s6, v0
	v_add_u32_e32 v0, 24, v110
	s_nop 0
	v_cndmask_b32_e32 v37, v248, v37, vcc
	v_cmp_lt_u32_e32 vcc, s6, v0
	v_add_u32_e32 v0, 51, v110
	s_nop 0
	v_cndmask_b32_e32 v53, v248, v53, vcc
	v_cmp_lt_u32_e32 vcc, s6, v0
	v_add_u32_e32 v0, 19, v110
	s_nop 0
	v_cndmask_b32_e32 v38, v248, v38, vcc
	v_cmp_lt_u32_e32 vcc, s6, v0
	v_add_u32_e32 v0, 50, v110
	s_nop 0
	v_cndmask_b32_e32 v54, v248, v54, vcc
	v_cmp_lt_u32_e32 vcc, s6, v0
	v_add_u32_e32 v0, 18, v110
	s_nop 0
	v_cndmask_b32_e32 v39, v248, v39, vcc
	v_cmp_lt_u32_e32 vcc, s6, v0
	v_add_u32_e32 v0, 49, v110
	s_nop 0
	v_cndmask_b32_e32 v55, v248, v55, vcc
	v_cmp_lt_u32_e32 vcc, s6, v0
	v_add_u32_e32 v0, 17, v110
	s_nop 0
	v_cndmask_b32_e32 v40, v248, v40, vcc
	v_cmp_lt_u32_e32 vcc, s6, v0
	v_add_u32_e32 v0, 48, v110
	s_nop 0
	v_cndmask_b32_e32 v56, v248, v56, vcc
	v_cmp_lt_u32_e32 vcc, s6, v0
	v_add_u32_e32 v0, 16, v110
	s_nop 0
	v_cndmask_b32_e32 v41, v248, v41, vcc
	v_cmp_lt_u32_e32 vcc, s6, v0
	v_add_u32_e32 v0, 43, v110
	s_nop 0
	v_cndmask_b32_e32 v57, v248, v57, vcc
	v_cmp_lt_u32_e32 vcc, s6, v0
	v_add_u32_e32 v0, 11, v110
	s_nop 0
	v_cndmask_b32_e32 v42, v248, v42, vcc
	v_cmp_lt_u32_e32 vcc, s6, v0
	v_add_u32_e32 v0, 42, v110
	s_nop 0
	v_cndmask_b32_e32 v58, v248, v58, vcc
	v_cmp_lt_u32_e32 vcc, s6, v0
	v_add_u32_e32 v0, 10, v110
	s_nop 0
	v_cndmask_b32_e32 v43, v248, v43, vcc
	v_cmp_lt_u32_e32 vcc, s6, v0
	v_add_u32_e32 v0, 41, v110
	s_nop 0
	v_cndmask_b32_e32 v59, v248, v59, vcc
	v_cmp_lt_u32_e32 vcc, s6, v0
	v_add_u32_e32 v0, 9, v110
	s_nop 0
	v_cndmask_b32_e32 v44, v248, v44, vcc
	v_cmp_lt_u32_e32 vcc, s6, v0
	v_add_u32_e32 v0, 40, v110
	s_nop 0
	v_cndmask_b32_e32 v60, v248, v60, vcc
	v_cmp_lt_u32_e32 vcc, s6, v0
	v_add_u32_e32 v0, 8, v110
	s_nop 0
	v_cndmask_b32_e32 v45, v248, v45, vcc
	v_cmp_lt_u32_e32 vcc, s6, v0
	v_add_u32_e32 v0, 35, v110
	s_nop 0
	v_cndmask_b32_e32 v61, v248, v61, vcc
	v_cmp_lt_u32_e32 vcc, s6, v0
	v_add_u32_e32 v0, 3, v110
	s_nop 0
	v_cndmask_b32_e32 v46, v248, v46, vcc
	v_cmp_lt_u32_e32 vcc, s6, v0
	v_add_u32_e32 v0, 34, v110
	s_nop 0
	v_cndmask_b32_e32 v62, v248, v62, vcc
	v_cmp_lt_u32_e32 vcc, s6, v0
	v_add_u32_e32 v0, 2, v110
	s_nop 0
	v_cndmask_b32_e32 v47, v248, v47, vcc
	v_cmp_lt_u32_e32 vcc, s6, v0
	v_add_u32_e32 v0, 33, v110
	s_nop 0
	v_cndmask_b32_e32 v63, v248, v63, vcc
	v_cmp_lt_u32_e32 vcc, s6, v0
	v_add_u32_e32 v0, 1, v110
	s_nop 0
	v_cndmask_b32_e32 v48, v248, v48, vcc
	v_cmp_lt_u32_e32 vcc, s6, v0
	v_add_u32_e32 v0, 32, v110
	s_nop 0
	v_cndmask_b32_e32 v64, v248, v64, vcc
	v_cmp_lt_u32_e32 vcc, s6, v0
	s_nop 1
	v_cndmask_b32_e32 v49, v248, v49, vcc
	v_cmp_lt_u32_e32 vcc, s6, v110
	s_nop 1
	v_cndmask_b32_e32 v65, v248, v65, vcc
.LBB0_466:
	s_nop 3
	v_max_f32_e32 v0, v35, v35
	v_max_f32_e32 v112, v34, v34
	v_max_f32_e32 v0, v112, v0
	v_max3_f32 v112, v36, v37, v51
	v_max3_f32 v0, v0, v50, v52
	v_max3_f32 v0, v0, v53, v38
	v_max3_f32 v112, v112, v40, v41
	v_max3_f32 v0, v0, v39, v54
	v_max3_f32 v112, v112, v56, v57
	v_max3_f32 v0, v0, v55, v42
	v_max3_f32 v112, v112, v44, v45
	v_max3_f32 v0, v0, v43, v58
	v_max3_f32 v112, v112, v60, v61
	v_max3_f32 v0, v0, v59, v46
	v_max3_f32 v112, v112, v48, v49
	v_max3_f32 v0, v0, v47, v62
	v_max3_f32 v112, v112, v64, v65
	v_and_b32_e32 v113, 64, v241
	v_max3_f32 v0, v0, v63, v112
	v_xor_b32_e32 v112, 32, v241
	v_add_u32_e32 v113, 64, v113
	v_cmp_lt_i32_e32 vcc, v112, v113
	s_nop 1
	v_cndmask_b32_e32 v115, v241, v112, vcc
	v_lshlrev_b32_e32 v115, 2, v115
	ds_bpermute_b32 v115, v115, v0
	s_waitcnt lgkmcnt(0)
	ds_read_b64_tr_b16 v[196:197], v234 offset:13376
	ds_read_b64_tr_b16 v[198:199], v234 offset:14912
	ds_read_b64_tr_b16 v[200:201], v234 offset:16448
	ds_read_b64_tr_b16 v[202:203], v234 offset:17984
	ds_read_b64_tr_b16 v[204:205], v234 offset:19520
	ds_read_b64_tr_b16 v[206:207], v234 offset:21056
	ds_read_b64_tr_b16 v[214:215], v234 offset:22592
	ds_read_b64_tr_b16 v[216:217], v234 offset:24128
	v_max_f32_e32 v115, v115, v115
	v_max_f32_e32 v0, v0, v115
	v_cmp_lt_f32_e32 vcc, s7, v0
	s_cbranch_vccz .LBB0_470
	v_max_f32_e32 v0, v0, v0
	v_max_f32_e32 v0, 0, v0
	v_add_f32_e32 v0, v114, v0
	v_cvt_pk_bf16_f32 v0, v0, v1
	s_nop 0
	v_lshlrev_b32_e32 v0, 16, v0
	s_and_saveexec_b64 s[10:11], s[36:37]
	s_cbranch_execz .LBB0_469
	v_xor_b32_e32 v115, 0x80000000, v0
	v_cvt_pk_bf16_f32 v115, v115, v1
	s_nop 0
	v_bfi_b32 v94, s2, v115, v94

.LBB0_471:
	v_exp_f32_e32 v34, v34
	v_exp_f32_e32 v35, v35
	v_exp_f32_e32 v36, v36
	v_exp_f32_e32 v37, v37
	v_exp_f32_e32 v38, v38
	v_exp_f32_e32 v39, v39
	v_exp_f32_e32 v40, v40
	v_exp_f32_e32 v41, v41
	v_cvt_pk_bf16_f32 v114, v34, v35
	v_cvt_pk_bf16_f32 v115, v36, v37
	v_cvt_pk_bf16_f32 v116, v38, v39
	v_cvt_pk_bf16_f32 v117, v40, v41
	v_exp_f32_e32 v42, v42
	v_exp_f32_e32 v43, v43
	v_mfma_f32_32x32x16_bf16 v[2:17], v[180:183], v[114:117], v[2:17]
	s_waitcnt lgkmcnt(6)
	v_mfma_f32_32x32x16_bf16 v[18:33], v[196:199], v[114:117], v[18:33]
	v_exp_f32_e32 v44, v44
	v_exp_f32_e32 v45, v45
	v_exp_f32_e32 v46, v46
	v_exp_f32_e32 v47, v47
	v_exp_f32_e32 v48, v48
	v_exp_f32_e32 v49, v49
	v_cvt_pk_bf16_f32 v122, v42, v43
	v_cvt_pk_bf16_f32 v123, v44, v45
	v_cvt_pk_bf16_f32 v124, v46, v47
	v_cvt_pk_bf16_f32 v125, v48, v49
	v_exp_f32_e32 v50, v50
	v_exp_f32_e32 v51, v51
	v_mfma_f32_32x32x16_bf16 v[2:17], v[184:187], v[122:125], v[2:17]
	s_waitcnt lgkmcnt(4)
	v_mfma_f32_32x32x16_bf16 v[18:33], v[200:203], v[122:125], v[18:33]
	v_exp_f32_e32 v52, v52
	v_exp_f32_e32 v53, v53
	v_exp_f32_e32 v54, v54
	v_exp_f32_e32 v55, v55
	v_exp_f32_e32 v56, v56
	v_exp_f32_e32 v57, v57
	v_cvt_pk_bf16_f32 v118, v50, v51
	v_cvt_pk_bf16_f32 v119, v52, v53
	v_cvt_pk_bf16_f32 v120, v54, v55
	v_cvt_pk_bf16_f32 v121, v56, v57
	v_exp_f32_e32 v58, v58
	v_exp_f32_e32 v59, v59
	v_mfma_f32_32x32x16_bf16 v[2:17], v[188:191], v[118:121], v[2:17]
	s_waitcnt lgkmcnt(2)
	v_mfma_f32_32x32x16_bf16 v[18:33], v[204:207], v[118:121], v[18:33]
	v_exp_f32_e32 v60, v60
	v_exp_f32_e32 v61, v61
	v_exp_f32_e32 v62, v62
	v_exp_f32_e32 v63, v63
	v_exp_f32_e32 v64, v64
	v_exp_f32_e32 v65, v65
	v_cvt_pk_bf16_f32 v126, v58, v59
	v_cvt_pk_bf16_f32 v127, v60, v61
	v_cvt_pk_bf16_f32 v128, v62, v63
	v_cvt_pk_bf16_f32 v129, v64, v65
	s_nop 1
	v_mfma_f32_32x32x16_bf16 v[2:17], v[192:195], v[126:129], v[2:17]
	s_waitcnt lgkmcnt(0)
	v_mfma_f32_32x32x16_bf16 v[18:33], v[214:217], v[126:129], v[18:33]
	s_andn2_b64 vcc, exec, s[16:17]
	s_cbranch_vccnz .LBB0_473
	s_bitcmp1_b32 s18, 0
	s_cselect_b32 s10, 0x6400, 0
	s_add_i32 s10, s10, 0
	v_add_u32_e32 v115, s10, v106
	v_add_u32_e32 v114, s10, v107
	s_waitcnt vmcnt(1)
	ds_write_b128 v115, v[86:89]
	s_waitcnt vmcnt(0)
	ds_write_b128 v114, v[90:93] offset:13312
